# UP epilogue: the leading half's alignment barrier taken after the row-statistics part (92 instructions overlap the trailing half's last MFMA block)
# speedup vs baseline: 1.0055x; 1.0055x over previous
.Lup_nopf:
	s_barrier
	s_setprio 1
	s_waitcnt lgkmcnt(0)
	v_mfma_f32_16x16x32_bf16 v[62:65], v[146:149], v[178:181], v[62:65]
	v_mfma_f32_16x16x32_bf16 v[58:61], v[154:157], v[178:181], v[58:61]
	v_mfma_f32_16x16x32_bf16 v[46:49], v[146:149], v[186:189], v[46:49]
	v_mfma_f32_16x16x32_bf16 v[42:45], v[154:157], v[186:189], v[42:45]
	v_mfma_f32_16x16x32_bf16 v[30:33], v[146:149], v[194:197], v[30:33]
	v_mfma_f32_16x16x32_bf16 v[26:29], v[154:157], v[194:197], v[26:29]
	v_mfma_f32_16x16x32_bf16 v[14:17], v[146:149], v[212:215], v[14:17]
	v_mfma_f32_16x16x32_bf16 v[10:13], v[154:157], v[212:215], v[10:13]
	v_mfma_f32_16x16x32_bf16 v[62:65], v[150:153], v[182:185], v[62:65]
	v_mfma_f32_16x16x32_bf16 v[58:61], v[158:161], v[182:185], v[58:61]
	v_mfma_f32_16x16x32_bf16 v[46:49], v[150:153], v[190:193], v[46:49]
	v_mfma_f32_16x16x32_bf16 v[42:45], v[158:161], v[190:193], v[42:45]
	v_mfma_f32_16x16x32_bf16 v[30:33], v[150:153], v[208:211], v[30:33]
	v_mfma_f32_16x16x32_bf16 v[26:29], v[158:161], v[208:211], v[26:29]
	v_mfma_f32_16x16x32_bf16 v[14:17], v[150:153], v[216:219], v[14:17]
	v_mfma_f32_16x16x32_bf16 v[10:13], v[158:161], v[216:219], v[10:13]
	s_setprio 0
	s_setprio 1
	v_mfma_f32_16x16x32_bf16 v[54:57], v[162:165], v[178:181], v[54:57]
	v_mfma_f32_16x16x32_bf16 v[50:53], v[170:173], v[178:181], v[50:53]
	v_mfma_f32_16x16x32_bf16 v[38:41], v[162:165], v[186:189], v[38:41]
	v_mfma_f32_16x16x32_bf16 v[34:37], v[170:173], v[186:189], v[34:37]
	v_mfma_f32_16x16x32_bf16 v[22:25], v[162:165], v[194:197], v[22:25]
	v_mfma_f32_16x16x32_bf16 v[18:21], v[170:173], v[194:197], v[18:21]
	v_mfma_f32_16x16x32_bf16 v[6:9], v[162:165], v[212:215], v[6:9]
	v_mfma_f32_16x16x32_bf16 v[2:5], v[170:173], v[212:215], v[2:5]
	v_mfma_f32_16x16x32_bf16 v[54:57], v[166:169], v[182:185], v[54:57]
	v_mfma_f32_16x16x32_bf16 v[50:53], v[174:177], v[182:185], v[50:53]
	v_mfma_f32_16x16x32_bf16 v[38:41], v[166:169], v[190:193], v[38:41]
	v_mfma_f32_16x16x32_bf16 v[34:37], v[174:177], v[190:193], v[34:37]
	v_mfma_f32_16x16x32_bf16 v[22:25], v[166:169], v[208:211], v[22:25]
	v_mfma_f32_16x16x32_bf16 v[18:21], v[174:177], v[208:211], v[18:21]
	v_mfma_f32_16x16x32_bf16 v[6:9], v[166:169], v[216:219], v[6:9]
	v_mfma_f32_16x16x32_bf16 v[2:5], v[174:177], v[216:219], v[2:5]
	s_setprio 0
	s_barrier
	s_add_i32 s51, s51, 2
	s_add_u32 s49, s49, 0x100
	s_addc_u32 s50, s50, 0
	s_add_u32 s38, s38, 0x100
	s_addc_u32 s39, s39, 0
	s_cmp_gt_u32 s51, 13
	s_cbranch_scc0 .LBB0_565
	s_lshl_b32 s19, s46, 8
	s_add_i32 s19, s19, s25
	v_lshl_or_b32 v184, s45, 7, v143
	s_waitcnt vmcnt(0)
	v_mov_b32_e32 v186, v233
	v_mov_b32_e32 v187, v234
	v_mov_b32_e32 v188, v235
	v_mov_b32_e32 v189, v236
	v_mov_b32_e32 v190, v237
	v_mov_b32_e32 v191, v238
	v_mov_b32_e32 v192, v239
	v_mov_b32_e32 v193, v240
	v_permlane16_swap_b32_e32 v233, v186
	v_permlane16_swap_b32_e32 v234, v187
	v_permlane16_swap_b32_e32 v235, v188
	v_permlane16_swap_b32_e32 v236, v189
	v_permlane16_swap_b32_e32 v237, v190
	v_permlane16_swap_b32_e32 v238, v191
	v_permlane16_swap_b32_e32 v239, v192
	v_permlane16_swap_b32_e32 v240, v193
	v_add_f32_e32 v208, v233, v186
	v_add_f32_e32 v209, v234, v187
	v_add_f32_e32 v210, v235, v188
	v_add_f32_e32 v211, v236, v189
	v_add_f32_e32 v212, v237, v190
	v_add_f32_e32 v213, v238, v191
	v_add_f32_e32 v214, v239, v192
	v_add_f32_e32 v215, v240, v193
	v_mov_b32_e32 v186, v208
	v_mov_b32_e32 v187, v209
	v_mov_b32_e32 v188, v210
	v_mov_b32_e32 v189, v211
	v_mov_b32_e32 v190, v212
	v_mov_b32_e32 v191, v213
	v_mov_b32_e32 v192, v214
	v_mov_b32_e32 v193, v215
	v_permlane32_swap_b32_e32 v208, v186
	v_permlane32_swap_b32_e32 v209, v187
	v_permlane32_swap_b32_e32 v210, v188
	v_permlane32_swap_b32_e32 v211, v189
	v_permlane32_swap_b32_e32 v212, v190
	v_permlane32_swap_b32_e32 v213, v191
	v_permlane32_swap_b32_e32 v214, v192
	v_permlane32_swap_b32_e32 v215, v193
	v_add_f32_e32 v208, v208, v186
	v_add_f32_e32 v209, v209, v187
	v_add_f32_e32 v210, v210, v188
	v_add_f32_e32 v211, v211, v189
	v_add_f32_e32 v212, v212, v190
	v_add_f32_e32 v213, v213, v191
	v_add_f32_e32 v214, v214, v192
	v_add_f32_e32 v215, v215, v193
	v_fmamk_f32 v208, v208, 0x3a800000, v222
	v_fmamk_f32 v209, v209, 0x3a800000, v222
	v_fmamk_f32 v210, v210, 0x3a800000, v222
	v_fmamk_f32 v211, v211, 0x3a800000, v222
	v_fmamk_f32 v212, v212, 0x3a800000, v222
	v_fmamk_f32 v213, v213, 0x3a800000, v222
	v_fmamk_f32 v214, v214, 0x3a800000, v222
	v_fmamk_f32 v215, v215, 0x3a800000, v222
	v_rsq_f32_e32 v208, v208
	v_rsq_f32_e32 v209, v209
	v_rsq_f32_e32 v210, v210
	v_rsq_f32_e32 v211, v211
	v_rsq_f32_e32 v212, v212
	v_rsq_f32_e32 v213, v213
	v_rsq_f32_e32 v214, v214
	v_rsq_f32_e32 v215, v215
	s_ashr_i32 s21, s19, 11
	s_mul_hi_i32 s39, s21, 0x1414000
	s_mul_i32 s21, s21, 0x1414000
	v_bitop3_b32 v149, s19, v230, v97 bitop3:0xc8
	s_add_u32 s38, s4, s21
	s_addc_u32 s39, s5, s39
	v_mul_u32_u24_e32 v0, 0xb00, v149
	v_lshlrev_b32_e32 v0, 1, v0
	v_lshl_add_u32 v220, v184, 1, v0
	v_mul_f32_e32 v232, v208, v208
	v_mul_f32_e32 v233, 0xbfb8aa3b, v208
	v_mul_f32_e32 v234, v209, v209
	v_mul_f32_e32 v235, 0xbfb8aa3b, v209
	v_mul_f32_e32 v236, v210, v210
	v_mul_f32_e32 v237, 0xbfb8aa3b, v210
	v_mul_f32_e32 v238, v211, v211
	v_mul_f32_e32 v239, 0xbfb8aa3b, v211
	v_mul_f32_e32 v240, v212, v212
	v_mul_f32_e32 v241, 0xbfb8aa3b, v212
	v_mul_f32_e32 v242, v213, v213
	v_mul_f32_e32 v243, 0xbfb8aa3b, v213
	v_mul_f32_e32 v244, v214, v214
	v_mul_f32_e32 v245, 0xbfb8aa3b, v214
	v_mul_f32_e32 v246, v215, v215
	v_mul_f32_e32 v247, 0xbfb8aa3b, v215
	s_and_b64 vcc, exec, s[10:11]
	s_cbranch_vccz .LBB0_568
	s_barrier
.LBB0_568:
	v_pk_mul_f32 v[208:209], v[130:131], v[232:233] op_sel:[0,1] op_sel_hi:[1,1]
	v_pk_mul_f32 v[210:211], v[132:133], v[232:233] op_sel:[0,1] op_sel_hi:[1,1]
	v_pk_mul_f32 v[212:213], v[126:127], v[232:233] op_sel:[0,1] op_sel_hi:[1,1]
	v_pk_mul_f32 v[214:215], v[128:129], v[232:233] op_sel:[0,1] op_sel_hi:[1,1]
	v_exp_f32_e32 v208, v208
	v_exp_f32_e32 v209, v209
	v_exp_f32_e32 v210, v210
	v_exp_f32_e32 v211, v211
	v_exp_f32_e32 v212, v212
	v_exp_f32_e32 v213, v213
	v_exp_f32_e32 v214, v214
	v_exp_f32_e32 v215, v215
	v_pk_add_f32 v[208:209], v[208:209], 1.0 op_sel_hi:[1,0]
	v_pk_add_f32 v[210:211], v[210:211], 1.0 op_sel_hi:[1,0]
	v_pk_add_f32 v[212:213], v[212:213], 1.0 op_sel_hi:[1,0]
	v_pk_add_f32 v[214:215], v[214:215], 1.0 op_sel_hi:[1,0]
	v_rcp_f32_e32 v208, v208
	v_rcp_f32_e32 v209, v209
	v_rcp_f32_e32 v210, v210
	v_rcp_f32_e32 v211, v211
	v_rcp_f32_e32 v212, v212
	v_rcp_f32_e32 v213, v213
	v_rcp_f32_e32 v214, v214
	v_rcp_f32_e32 v215, v215
	v_pk_mul_f32 v[130:131], v[130:131], v[122:123]
	v_pk_mul_f32 v[132:133], v[132:133], v[124:125]
	v_pk_mul_f32 v[126:127], v[126:127], v[118:119]
	v_pk_mul_f32 v[128:129], v[128:129], v[120:121]
	v_pk_mul_f32 v[208:209], v[208:209], v[232:233] op_sel_hi:[1,0]
	v_pk_mul_f32 v[210:211], v[210:211], v[232:233] op_sel_hi:[1,0]
	v_pk_mul_f32 v[212:213], v[212:213], v[232:233] op_sel_hi:[1,0]
	v_pk_mul_f32 v[214:215], v[214:215], v[232:233] op_sel_hi:[1,0]
	v_pk_mul_f32 v[130:131], v[130:131], v[208:209]
	v_pk_mul_f32 v[132:133], v[132:133], v[210:211]
	v_pk_mul_f32 v[126:127], v[126:127], v[212:213]
	v_pk_mul_f32 v[128:129], v[128:129], v[214:215]
	v_cvt_pk_bf16_f32 v216, v130, v131
	v_cvt_pk_bf16_f32 v217, v132, v133
	v_cvt_pk_bf16_f32 v218, v126, v127
	v_cvt_pk_bf16_f32 v219, v128, v129
	global_store_dwordx4 v220, v[216:219], s[38:39]
	v_pk_mul_f32 v[208:209], v[114:115], v[234:235] op_sel:[0,1] op_sel_hi:[1,1]
	v_pk_mul_f32 v[210:211], v[116:117], v[234:235] op_sel:[0,1] op_sel_hi:[1,1]
	v_pk_mul_f32 v[212:213], v[110:111], v[234:235] op_sel:[0,1] op_sel_hi:[1,1]
	v_pk_mul_f32 v[214:215], v[112:113], v[234:235] op_sel:[0,1] op_sel_hi:[1,1]
	v_exp_f32_e32 v208, v208
	v_exp_f32_e32 v209, v209
	v_exp_f32_e32 v210, v210
	v_exp_f32_e32 v211, v211
	v_exp_f32_e32 v212, v212
	v_exp_f32_e32 v213, v213
	v_exp_f32_e32 v214, v214
	v_exp_f32_e32 v215, v215
	v_pk_add_f32 v[208:209], v[208:209], 1.0 op_sel_hi:[1,0]
	v_pk_add_f32 v[210:211], v[210:211], 1.0 op_sel_hi:[1,0]
	v_pk_add_f32 v[212:213], v[212:213], 1.0 op_sel_hi:[1,0]
	v_pk_add_f32 v[214:215], v[214:215], 1.0 op_sel_hi:[1,0]
	v_rcp_f32_e32 v208, v208
	v_rcp_f32_e32 v209, v209
	v_rcp_f32_e32 v210, v210
	v_rcp_f32_e32 v211, v211
	v_rcp_f32_e32 v212, v212
	v_rcp_f32_e32 v213, v213
	v_rcp_f32_e32 v214, v214
	v_rcp_f32_e32 v215, v215
	v_pk_mul_f32 v[114:115], v[114:115], v[106:107]
	v_pk_mul_f32 v[116:117], v[116:117], v[108:109]
	v_pk_mul_f32 v[110:111], v[110:111], v[102:103]
	v_pk_mul_f32 v[112:113], v[112:113], v[104:105]
	v_pk_mul_f32 v[208:209], v[208:209], v[234:235] op_sel_hi:[1,0]
	v_pk_mul_f32 v[210:211], v[210:211], v[234:235] op_sel_hi:[1,0]
	v_pk_mul_f32 v[212:213], v[212:213], v[234:235] op_sel_hi:[1,0]
	v_pk_mul_f32 v[214:215], v[214:215], v[234:235] op_sel_hi:[1,0]
	v_pk_mul_f32 v[114:115], v[114:115], v[208:209]
	v_pk_mul_f32 v[116:117], v[116:117], v[210:211]
	v_pk_mul_f32 v[110:111], v[110:111], v[212:213]
	v_pk_mul_f32 v[112:113], v[112:113], v[214:215]
	v_cvt_pk_bf16_f32 v248, v114, v115
	v_cvt_pk_bf16_f32 v249, v116, v117
	v_cvt_pk_bf16_f32 v250, v110, v111
	v_cvt_pk_bf16_f32 v251, v112, v113
	v_add_u32_e32 v221, 0x16000, v220
	global_store_dwordx4 v221, v[248:251], s[38:39]
	v_pk_mul_f32 v[208:209], v[98:99], v[236:237] op_sel:[0,1] op_sel_hi:[1,1]
	v_pk_mul_f32 v[210:211], v[100:101], v[236:237] op_sel:[0,1] op_sel_hi:[1,1]
	v_pk_mul_f32 v[212:213], v[90:91], v[236:237] op_sel:[0,1] op_sel_hi:[1,1]
	v_pk_mul_f32 v[214:215], v[92:93], v[236:237] op_sel:[0,1] op_sel_hi:[1,1]
	v_exp_f32_e32 v208, v208
	v_exp_f32_e32 v209, v209
	v_exp_f32_e32 v210, v210
	v_exp_f32_e32 v211, v211
	v_exp_f32_e32 v212, v212
	v_exp_f32_e32 v213, v213
	v_exp_f32_e32 v214, v214
	v_exp_f32_e32 v215, v215
	v_pk_add_f32 v[208:209], v[208:209], 1.0 op_sel_hi:[1,0]
	v_pk_add_f32 v[210:211], v[210:211], 1.0 op_sel_hi:[1,0]
	v_pk_add_f32 v[212:213], v[212:213], 1.0 op_sel_hi:[1,0]
	v_pk_add_f32 v[214:215], v[214:215], 1.0 op_sel_hi:[1,0]
	v_rcp_f32_e32 v208, v208
	v_rcp_f32_e32 v209, v209
	v_rcp_f32_e32 v210, v210
	v_rcp_f32_e32 v211, v211
	v_rcp_f32_e32 v212, v212
	v_rcp_f32_e32 v213, v213
	v_rcp_f32_e32 v214, v214
	v_rcp_f32_e32 v215, v215
	v_pk_mul_f32 v[98:99], v[98:99], v[86:87]
	v_pk_mul_f32 v[100:101], v[100:101], v[88:89]
	v_pk_mul_f32 v[90:91], v[90:91], v[82:83]
	v_pk_mul_f32 v[92:93], v[92:93], v[84:85]
	v_pk_mul_f32 v[208:209], v[208:209], v[236:237] op_sel_hi:[1,0]
	v_pk_mul_f32 v[210:211], v[210:211], v[236:237] op_sel_hi:[1,0]
	v_pk_mul_f32 v[212:213], v[212:213], v[236:237] op_sel_hi:[1,0]
	v_pk_mul_f32 v[214:215], v[214:215], v[236:237] op_sel_hi:[1,0]
	v_pk_mul_f32 v[98:99], v[98:99], v[208:209]
	v_pk_mul_f32 v[100:101], v[100:101], v[210:211]
	v_pk_mul_f32 v[90:91], v[90:91], v[212:213]
	v_pk_mul_f32 v[92:93], v[92:93], v[214:215]
	v_cvt_pk_bf16_f32 v216, v98, v99
	v_cvt_pk_bf16_f32 v217, v100, v101
	v_cvt_pk_bf16_f32 v218, v90, v91
	v_cvt_pk_bf16_f32 v219, v92, v93
	v_add_u32_e32 v221, 0x2c000, v220
	global_store_dwordx4 v221, v[216:219], s[38:39]
	v_pk_mul_f32 v[208:209], v[78:79], v[238:239] op_sel:[0,1] op_sel_hi:[1,1]
	v_pk_mul_f32 v[210:211], v[80:81], v[238:239] op_sel:[0,1] op_sel_hi:[1,1]
	v_pk_mul_f32 v[212:213], v[74:75], v[238:239] op_sel:[0,1] op_sel_hi:[1,1]
	v_pk_mul_f32 v[214:215], v[76:77], v[238:239] op_sel:[0,1] op_sel_hi:[1,1]
	v_exp_f32_e32 v208, v208
	v_exp_f32_e32 v209, v209
	v_exp_f32_e32 v210, v210
	v_exp_f32_e32 v211, v211
	v_exp_f32_e32 v212, v212
	v_exp_f32_e32 v213, v213
	v_exp_f32_e32 v214, v214
	v_exp_f32_e32 v215, v215
	v_pk_add_f32 v[208:209], v[208:209], 1.0 op_sel_hi:[1,0]
	v_pk_add_f32 v[210:211], v[210:211], 1.0 op_sel_hi:[1,0]
	v_pk_add_f32 v[212:213], v[212:213], 1.0 op_sel_hi:[1,0]
	v_pk_add_f32 v[214:215], v[214:215], 1.0 op_sel_hi:[1,0]
	v_rcp_f32_e32 v208, v208
	v_rcp_f32_e32 v209, v209
	v_rcp_f32_e32 v210, v210
	v_rcp_f32_e32 v211, v211
	v_rcp_f32_e32 v212, v212
	v_rcp_f32_e32 v213, v213
	v_rcp_f32_e32 v214, v214
	v_rcp_f32_e32 v215, v215
	v_pk_mul_f32 v[78:79], v[78:79], v[70:71]
	v_pk_mul_f32 v[80:81], v[80:81], v[72:73]
	v_pk_mul_f32 v[74:75], v[74:75], v[66:67]
	v_pk_mul_f32 v[76:77], v[76:77], v[68:69]
	v_pk_mul_f32 v[208:209], v[208:209], v[238:239] op_sel_hi:[1,0]
	v_pk_mul_f32 v[210:211], v[210:211], v[238:239] op_sel_hi:[1,0]
	v_pk_mul_f32 v[212:213], v[212:213], v[238:239] op_sel_hi:[1,0]
	v_pk_mul_f32 v[214:215], v[214:215], v[238:239] op_sel_hi:[1,0]
	v_pk_mul_f32 v[78:79], v[78:79], v[208:209]
	v_pk_mul_f32 v[80:81], v[80:81], v[210:211]
	v_pk_mul_f32 v[74:75], v[74:75], v[212:213]
	v_pk_mul_f32 v[76:77], v[76:77], v[214:215]
	v_cvt_pk_bf16_f32 v248, v78, v79
	v_cvt_pk_bf16_f32 v249, v80, v81
	v_cvt_pk_bf16_f32 v250, v74, v75
	v_cvt_pk_bf16_f32 v251, v76, v77
	v_add_u32_e32 v221, 0x42000, v220
	global_store_dwordx4 v221, v[248:251], s[38:39]
	v_pk_mul_f32 v[208:209], v[62:63], v[240:241] op_sel:[0,1] op_sel_hi:[1,1]
	v_pk_mul_f32 v[210:211], v[64:65], v[240:241] op_sel:[0,1] op_sel_hi:[1,1]
	v_pk_mul_f32 v[212:213], v[58:59], v[240:241] op_sel:[0,1] op_sel_hi:[1,1]
	v_pk_mul_f32 v[214:215], v[60:61], v[240:241] op_sel:[0,1] op_sel_hi:[1,1]
	v_exp_f32_e32 v208, v208
	v_exp_f32_e32 v209, v209
	v_exp_f32_e32 v210, v210
	v_exp_f32_e32 v211, v211
	v_exp_f32_e32 v212, v212
	v_exp_f32_e32 v213, v213
	v_exp_f32_e32 v214, v214
	v_exp_f32_e32 v215, v215
	v_pk_add_f32 v[208:209], v[208:209], 1.0 op_sel_hi:[1,0]
	v_pk_add_f32 v[210:211], v[210:211], 1.0 op_sel_hi:[1,0]
	v_pk_add_f32 v[212:213], v[212:213], 1.0 op_sel_hi:[1,0]
	v_pk_add_f32 v[214:215], v[214:215], 1.0 op_sel_hi:[1,0]
	v_rcp_f32_e32 v208, v208
	v_rcp_f32_e32 v209, v209
	v_rcp_f32_e32 v210, v210
	v_rcp_f32_e32 v211, v211
	v_rcp_f32_e32 v212, v212
	v_rcp_f32_e32 v213, v213
	v_rcp_f32_e32 v214, v214
	v_rcp_f32_e32 v215, v215
	v_pk_mul_f32 v[62:63], v[62:63], v[54:55]
	v_pk_mul_f32 v[64:65], v[64:65], v[56:57]
	v_pk_mul_f32 v[58:59], v[58:59], v[50:51]
	v_pk_mul_f32 v[60:61], v[60:61], v[52:53]
	v_pk_mul_f32 v[208:209], v[208:209], v[240:241] op_sel_hi:[1,0]
	v_pk_mul_f32 v[210:211], v[210:211], v[240:241] op_sel_hi:[1,0]
	v_pk_mul_f32 v[212:213], v[212:213], v[240:241] op_sel_hi:[1,0]
	v_pk_mul_f32 v[214:215], v[214:215], v[240:241] op_sel_hi:[1,0]
	v_pk_mul_f32 v[62:63], v[62:63], v[208:209]
	v_pk_mul_f32 v[64:65], v[64:65], v[210:211]
	v_pk_mul_f32 v[58:59], v[58:59], v[212:213]
	v_pk_mul_f32 v[60:61], v[60:61], v[214:215]
	v_cvt_pk_bf16_f32 v216, v62, v63
	v_cvt_pk_bf16_f32 v217, v64, v65
	v_cvt_pk_bf16_f32 v218, v58, v59
	v_cvt_pk_bf16_f32 v219, v60, v61
	v_add_u32_e32 v221, 0xb0000, v220
	global_store_dwordx4 v221, v[216:219], s[38:39]
	v_pk_mul_f32 v[208:209], v[46:47], v[242:243] op_sel:[0,1] op_sel_hi:[1,1]
	v_pk_mul_f32 v[210:211], v[48:49], v[242:243] op_sel:[0,1] op_sel_hi:[1,1]
	v_pk_mul_f32 v[212:213], v[42:43], v[242:243] op_sel:[0,1] op_sel_hi:[1,1]
	v_pk_mul_f32 v[214:215], v[44:45], v[242:243] op_sel:[0,1] op_sel_hi:[1,1]
	v_exp_f32_e32 v208, v208
	v_exp_f32_e32 v209, v209
	v_exp_f32_e32 v210, v210
	v_exp_f32_e32 v211, v211
	v_exp_f32_e32 v212, v212
	v_exp_f32_e32 v213, v213
	v_exp_f32_e32 v214, v214
	v_exp_f32_e32 v215, v215
	v_pk_add_f32 v[208:209], v[208:209], 1.0 op_sel_hi:[1,0]
	v_pk_add_f32 v[210:211], v[210:211], 1.0 op_sel_hi:[1,0]
	v_pk_add_f32 v[212:213], v[212:213], 1.0 op_sel_hi:[1,0]
	v_pk_add_f32 v[214:215], v[214:215], 1.0 op_sel_hi:[1,0]
	v_rcp_f32_e32 v208, v208
	v_rcp_f32_e32 v209, v209
	v_rcp_f32_e32 v210, v210
	v_rcp_f32_e32 v211, v211
	v_rcp_f32_e32 v212, v212
	v_rcp_f32_e32 v213, v213
	v_rcp_f32_e32 v214, v214
	v_rcp_f32_e32 v215, v215
	v_pk_mul_f32 v[46:47], v[46:47], v[38:39]
	v_pk_mul_f32 v[48:49], v[48:49], v[40:41]
	v_pk_mul_f32 v[42:43], v[42:43], v[34:35]
	v_pk_mul_f32 v[44:45], v[44:45], v[36:37]
	v_pk_mul_f32 v[208:209], v[208:209], v[242:243] op_sel_hi:[1,0]
	v_pk_mul_f32 v[210:211], v[210:211], v[242:243] op_sel_hi:[1,0]
	v_pk_mul_f32 v[212:213], v[212:213], v[242:243] op_sel_hi:[1,0]
	v_pk_mul_f32 v[214:215], v[214:215], v[242:243] op_sel_hi:[1,0]
	v_pk_mul_f32 v[46:47], v[46:47], v[208:209]
	v_pk_mul_f32 v[48:49], v[48:49], v[210:211]
	v_pk_mul_f32 v[42:43], v[42:43], v[212:213]
	v_pk_mul_f32 v[44:45], v[44:45], v[214:215]
	v_cvt_pk_bf16_f32 v248, v46, v47
	v_cvt_pk_bf16_f32 v249, v48, v49
	v_cvt_pk_bf16_f32 v250, v42, v43
	v_cvt_pk_bf16_f32 v251, v44, v45
	v_add_u32_e32 v221, 0xc6000, v220
	global_store_dwordx4 v221, v[248:251], s[38:39]
	v_pk_mul_f32 v[208:209], v[30:31], v[244:245] op_sel:[0,1] op_sel_hi:[1,1]
	v_pk_mul_f32 v[210:211], v[32:33], v[244:245] op_sel:[0,1] op_sel_hi:[1,1]
	v_pk_mul_f32 v[212:213], v[26:27], v[244:245] op_sel:[0,1] op_sel_hi:[1,1]
	v_pk_mul_f32 v[214:215], v[28:29], v[244:245] op_sel:[0,1] op_sel_hi:[1,1]
	v_exp_f32_e32 v208, v208
	v_exp_f32_e32 v209, v209
	v_exp_f32_e32 v210, v210
	v_exp_f32_e32 v211, v211
	v_exp_f32_e32 v212, v212
	v_exp_f32_e32 v213, v213
	v_exp_f32_e32 v214, v214
	v_exp_f32_e32 v215, v215
	v_pk_add_f32 v[208:209], v[208:209], 1.0 op_sel_hi:[1,0]
	v_pk_add_f32 v[210:211], v[210:211], 1.0 op_sel_hi:[1,0]
	v_pk_add_f32 v[212:213], v[212:213], 1.0 op_sel_hi:[1,0]
	v_pk_add_f32 v[214:215], v[214:215], 1.0 op_sel_hi:[1,0]
	v_rcp_f32_e32 v208, v208
	v_rcp_f32_e32 v209, v209
	v_rcp_f32_e32 v210, v210
	v_rcp_f32_e32 v211, v211
	v_rcp_f32_e32 v212, v212
	v_rcp_f32_e32 v213, v213
	v_rcp_f32_e32 v214, v214
	v_rcp_f32_e32 v215, v215
	v_pk_mul_f32 v[30:31], v[30:31], v[22:23]
	v_pk_mul_f32 v[32:33], v[32:33], v[24:25]
	v_pk_mul_f32 v[26:27], v[26:27], v[18:19]
	v_pk_mul_f32 v[28:29], v[28:29], v[20:21]
	v_pk_mul_f32 v[208:209], v[208:209], v[244:245] op_sel_hi:[1,0]
	v_pk_mul_f32 v[210:211], v[210:211], v[244:245] op_sel_hi:[1,0]
	v_pk_mul_f32 v[212:213], v[212:213], v[244:245] op_sel_hi:[1,0]
	v_pk_mul_f32 v[214:215], v[214:215], v[244:245] op_sel_hi:[1,0]
	v_pk_mul_f32 v[30:31], v[30:31], v[208:209]
	v_pk_mul_f32 v[32:33], v[32:33], v[210:211]
	v_pk_mul_f32 v[26:27], v[26:27], v[212:213]
	v_pk_mul_f32 v[28:29], v[28:29], v[214:215]
	v_cvt_pk_bf16_f32 v216, v30, v31
	v_cvt_pk_bf16_f32 v217, v32, v33
	v_cvt_pk_bf16_f32 v218, v26, v27
	v_cvt_pk_bf16_f32 v219, v28, v29
	v_add_u32_e32 v221, 0xdc000, v220
	global_store_dwordx4 v221, v[216:219], s[38:39]
	v_pk_mul_f32 v[208:209], v[14:15], v[246:247] op_sel:[0,1] op_sel_hi:[1,1]
	v_pk_mul_f32 v[210:211], v[16:17], v[246:247] op_sel:[0,1] op_sel_hi:[1,1]
	v_pk_mul_f32 v[212:213], v[10:11], v[246:247] op_sel:[0,1] op_sel_hi:[1,1]
	v_pk_mul_f32 v[214:215], v[12:13], v[246:247] op_sel:[0,1] op_sel_hi:[1,1]
	v_exp_f32_e32 v208, v208
	v_exp_f32_e32 v209, v209
	v_exp_f32_e32 v210, v210
	v_exp_f32_e32 v211, v211
	v_exp_f32_e32 v212, v212
	v_exp_f32_e32 v213, v213
	v_exp_f32_e32 v214, v214
	v_exp_f32_e32 v215, v215
	v_pk_add_f32 v[208:209], v[208:209], 1.0 op_sel_hi:[1,0]
	v_pk_add_f32 v[210:211], v[210:211], 1.0 op_sel_hi:[1,0]
	v_pk_add_f32 v[212:213], v[212:213], 1.0 op_sel_hi:[1,0]
	v_pk_add_f32 v[214:215], v[214:215], 1.0 op_sel_hi:[1,0]
	v_rcp_f32_e32 v208, v208
	v_rcp_f32_e32 v209, v209
	v_rcp_f32_e32 v210, v210
	v_rcp_f32_e32 v211, v211
	v_rcp_f32_e32 v212, v212
	v_rcp_f32_e32 v213, v213
	v_rcp_f32_e32 v214, v214
	v_rcp_f32_e32 v215, v215
	v_pk_mul_f32 v[14:15], v[14:15], v[6:7]
	v_pk_mul_f32 v[16:17], v[16:17], v[8:9]
	v_pk_mul_f32 v[10:11], v[10:11], v[2:3]
	v_pk_mul_f32 v[12:13], v[12:13], v[4:5]
	v_pk_mul_f32 v[208:209], v[208:209], v[246:247] op_sel_hi:[1,0]
	v_pk_mul_f32 v[210:211], v[210:211], v[246:247] op_sel_hi:[1,0]
	v_pk_mul_f32 v[212:213], v[212:213], v[246:247] op_sel_hi:[1,0]
	v_pk_mul_f32 v[214:215], v[214:215], v[246:247] op_sel_hi:[1,0]
	v_pk_mul_f32 v[14:15], v[14:15], v[208:209]
	v_pk_mul_f32 v[16:17], v[16:17], v[210:211]
	v_pk_mul_f32 v[10:11], v[10:11], v[212:213]
	v_pk_mul_f32 v[12:13], v[12:13], v[214:215]
	v_cvt_pk_bf16_f32 v248, v14, v15
	v_cvt_pk_bf16_f32 v249, v16, v17
	v_cvt_pk_bf16_f32 v250, v10, v11
	v_cvt_pk_bf16_f32 v251, v12, v13
	v_add_u32_e32 v221, 0xf2000, v220
	global_store_dwordx4 v221, v[248:251], s[38:39]
	s_mov_b32 s21, 0x16000
	s_mov_b32 s40, 0x2c000
	s_mov_b32 s19, 0x1414000
	s_andn2_b64 vcc, exec, s[36:37]
	s_mov_b64 s[36:37], -1
	s_cbranch_vccnz .LBB0_561
	s_andn2_b64 vcc, exec, s[0:1]
	s_cbranch_vccnz .LBB0_560
	s_barrier
	s_branch .LBB0_560
